# attention loop: K LDS-DMA issues spread into the first QK^T chain's MFMA gaps, V LDS-DMA issues into the wait states behind it
# baseline (speedup 1.0000x reference)
.LBB0_429:
	s_mov_b32 s46, s75
	s_mov_b32 s47, s74
	s_mov_b32 s49, s51
	v_lshl_add_u32 v0, s48, 1, v218
	s_lshl_b32 s48, s76, 1
	v_add_u32_e32 v14, s48, v228
	ds_read_b128 v[2:5], v14 offset:4096
	ds_read_b128 v[6:9], v14 offset:6144
	ds_read_b64_tr_b16 v[10:11], v0
	ds_read_b64_tr_b16 v[12:13], v0 offset:512
	s_waitcnt lgkmcnt(5)
	v_mfma_f32_32x32x16_bf16 v[92:107], v[156:159], v[120:123], 0
	s_add_u32 s74, s44, 0xff020000
	s_addc_u32 s75, s45, -1
	s_lshl_b32 s51, s77, 1
	s_add_i32 s51, s51, s72
	s_mov_b32 s76, m0
	s_mov_b32 m0, s51
	s_nop 0
	global_load_lds_dwordx4 v226, s[74:75]
	s_mov_b32 m0, s76
	ds_read_b128 v[80:83], v14 offset:512
	ds_read_b128 v[156:159], v14 offset:2560
	ds_read_b64_tr_b16 v[164:165], v0 offset:4096
	ds_read_b64_tr_b16 v[166:167], v0 offset:4608
	s_waitcnt lgkmcnt(8)
	v_mfma_f32_32x32x16_bf16 v[92:107], v[160:163], v[116:119], v[92:107]
	s_add_u32 s74, s44, 0xff020080
	s_addc_u32 s75, s45, -1
	s_addk_i32 s51, 0x2000
	s_mov_b32 s76, m0
	s_mov_b32 m0, s51
	s_nop 0
	global_load_lds_dwordx4 v226, s[74:75]
	s_mov_b32 m0, s76
	ds_read_b128 v[160:163], v14 offset:4608
	ds_read_b128 v[168:171], v14 offset:6656
	ds_read_b64_tr_b16 v[172:173], v0 offset:1024
	ds_read_b64_tr_b16 v[174:175], v0 offset:1536
	s_waitcnt lgkmcnt(11)
	v_mfma_f32_32x32x16_bf16 v[92:107], v[2:5], v[112:115], v[92:107]
	ds_read_b64_tr_b16 v[2:3], v0 offset:5120
	ds_read_b64_tr_b16 v[4:5], v0 offset:5632
	s_waitcnt lgkmcnt(12)
	v_mfma_f32_32x32x16_bf16 v[92:107], v[6:9], v[108:111], v[92:107]
	s_add_u32 s74, s44, 0xfffe0000
	s_addc_u32 s75, s45, -1
	s_lshl_b32 s51, s47, 1
	s_add_i32 s51, s51, s73
	s_mov_b32 s76, m0
	s_mov_b32 m0, s51
	s_nop 0
	global_load_lds_dwordx4 v227, s[74:75]
	s_mov_b32 m0, s76
	s_add_u32 s74, s44, 0xfffe0080
	s_addc_u32 s75, s45, -1
	s_addk_i32 s51, 0x2000
	s_mov_b32 s76, m0
	s_mov_b32 m0, s51
	s_nop 0
	global_load_lds_dwordx4 v227, s[74:75]
	s_mov_b32 m0, s76
	v_exp_f32_e32 v14, v92
	v_exp_f32_e32 v15, v93
	v_exp_f32_e32 v124, v94
	v_exp_f32_e32 v128, v95
	s_waitcnt lgkmcnt(9)
	v_mfma_f32_32x32x16_bf16 v[80:95], v[80:83], v[120:123], 0
	ds_read_b64_tr_b16 v[6:7], v0 offset:2048
	ds_read_b64_tr_b16 v[8:9], v0 offset:2560
	v_add_f32_e32 v132, 0, v14
	v_add_f32_e32 v132, v15, v132
	v_add_f32_e32 v132, v124, v132
	v_add_f32_e32 v132, v128, v132
	v_cvt_pk_bf16_f32 v136, v14, v15
	v_cvt_pk_bf16_f32 v137, v124, v128
	v_exp_f32_e32 v14, v96
	v_exp_f32_e32 v15, v97
	v_exp_f32_e32 v124, v98
	s_waitcnt lgkmcnt(10)
	v_mfma_f32_32x32x16_bf16 v[80:95], v[156:159], v[116:119], v[80:95]
	v_exp_f32_e32 v128, v99
	ds_read_b64_tr_b16 v[96:97], v0 offset:6144
	ds_read_b64_tr_b16 v[98:99], v0 offset:6656
	v_add_f32_e32 v132, v14, v132
	v_add_f32_e32 v132, v15, v132
	v_add_f32_e32 v132, v124, v132
	v_add_f32_e32 v132, v128, v132
	v_cvt_pk_bf16_f32 v138, v14, v15
	v_cvt_pk_bf16_f32 v139, v124, v128
	v_exp_f32_e32 v14, v100
	v_exp_f32_e32 v15, v101
	v_exp_f32_e32 v124, v102
	s_waitcnt lgkmcnt(9)
	v_mfma_f32_32x32x16_bf16 v[80:95], v[160:163], v[112:115], v[80:95]
	v_exp_f32_e32 v128, v103
	ds_read_b64_tr_b16 v[100:101], v0 offset:3072
	ds_read_b64_tr_b16 v[102:103], v0 offset:3584
	v_add_f32_e32 v132, v14, v132
	v_add_f32_e32 v132, v15, v132
	v_add_f32_e32 v132, v124, v132
	v_add_f32_e32 v156, v128, v132
	v_cvt_pk_bf16_f32 v132, v14, v15
	v_cvt_pk_bf16_f32 v133, v124, v128
	v_exp_f32_e32 v14, v104
	v_exp_f32_e32 v15, v105
	v_exp_f32_e32 v124, v106
	s_waitcnt lgkmcnt(10)
	v_mfma_f32_32x32x16_bf16 v[80:95], v[168:171], v[108:111], v[80:95]
	v_exp_f32_e32 v128, v107
	ds_read_b64_tr_b16 v[104:105], v0 offset:7168
	ds_read_b64_tr_b16 v[106:107], v0 offset:7680
	v_add_f32_e32 v134, v14, v156
	v_add_f32_e32 v134, v15, v134
	v_add_f32_e32 v134, v124, v134
	v_add_f32_e32 v156, v128, v134
	v_cvt_pk_bf16_f32 v134, v14, v15
	v_cvt_pk_bf16_f32 v135, v124, v128
	s_nop 1
	v_mfma_f32_32x32x16_bf16 v[16:31], v[152:155], v[10:13], v[16:31]
	v_exp_f32_e32 v14, v80
	ds_read_b64_tr_b16 v[10:11], v0 offset:8192
	ds_read_b64_tr_b16 v[12:13], v0 offset:8704
	v_exp_f32_e32 v15, v81
	v_mov_b32_e32 v80, v14
	v_add_f32_e32 v14, v14, v156
	s_nop 0
	v_cvt_pk_bf16_f32 v128, v80, v15
	v_mfma_f32_32x32x16_bf16 v[32:47], v[152:155], v[164:167], v[32:47]
	ds_read_b64_tr_b16 v[156:157], v0 offset:12288
	ds_read_b64_tr_b16 v[158:159], v0 offset:12800
	v_add_f32_e32 v14, v15, v14
	s_waitcnt lgkmcnt(14)
	v_mfma_f32_32x32x16_bf16 v[16:31], v[148:151], v[172:175], v[16:31]
	v_exp_f32_e32 v15, v82
	ds_read_b64_tr_b16 v[160:161], v0 offset:9216
	ds_read_b64_tr_b16 v[162:163], v0 offset:9728
	v_add_f32_e32 v14, v15, v14
	s_waitcnt lgkmcnt(14)
	v_mfma_f32_32x32x16_bf16 v[32:47], v[148:151], v[2:5], v[32:47]
	v_exp_f32_e32 v80, v83
	ds_read_b64_tr_b16 v[2:3], v0 offset:13312
	ds_read_b64_tr_b16 v[4:5], v0 offset:13824
	v_add_f32_e32 v14, v80, v14
	v_cvt_pk_bf16_f32 v129, v15, v80
	s_waitcnt lgkmcnt(14)
	v_mfma_f32_32x32x16_bf16 v[16:31], v[144:147], v[6:9], v[16:31]
	v_exp_f32_e32 v15, v84
	ds_read_b64_tr_b16 v[6:7], v0 offset:10240
	ds_read_b64_tr_b16 v[8:9], v0 offset:10752
	v_add_f32_e32 v14, v15, v14
	s_waitcnt lgkmcnt(14)
	v_mfma_f32_32x32x16_bf16 v[32:47], v[144:147], v[96:99], v[32:47]
	v_exp_f32_e32 v84, v85
	ds_read_b64_tr_b16 v[80:81], v0 offset:14336
	ds_read_b64_tr_b16 v[82:83], v0 offset:14848
	v_add_f32_e32 v14, v84, v14
	v_cvt_pk_bf16_f32 v130, v15, v84
	s_waitcnt lgkmcnt(14)
	v_mfma_f32_32x32x16_bf16 v[16:31], v[140:143], v[100:103], v[16:31]
	v_exp_f32_e32 v15, v86
	ds_read_b64_tr_b16 v[96:97], v0 offset:11264
	ds_read_b64_tr_b16 v[98:99], v0 offset:11776
	v_add_f32_e32 v14, v15, v14
	s_waitcnt lgkmcnt(14)
	v_mfma_f32_32x32x16_bf16 v[32:47], v[140:143], v[104:107], v[32:47]
	v_exp_f32_e32 v100, v87
	ds_read_b64_tr_b16 v[84:85], v0 offset:15360
	ds_read_b64_tr_b16 v[86:87], v0 offset:15872
	v_add_f32_e32 v0, v100, v14
	v_cvt_pk_bf16_f32 v131, v15, v100
	v_exp_f32_e32 v14, v88
	v_exp_f32_e32 v15, v89
	s_waitcnt lgkmcnt(14)
	v_mfma_f32_32x32x16_bf16 v[48:63], v[152:155], v[10:13], v[48:63]
	v_lshl_add_u32 v88, s46, 1, v228
	v_mov_b32_e32 v89, v14
	v_add_f32_e32 v0, v14, v0
	s_nop 0
	v_cvt_pk_bf16_f32 v124, v89, v15
	s_waitcnt lgkmcnt(12)
	v_mfma_f32_32x32x16_bf16 v[64:79], v[152:155], v[156:159], v[64:79]
	v_add_f32_e32 v0, v15, v0
	v_exp_f32_e32 v10, v90
	s_waitcnt lgkmcnt(10)
	v_mfma_f32_32x32x16_bf16 v[48:63], v[148:151], v[160:163], v[48:63]
	v_add_f32_e32 v0, v10, v0
	v_exp_f32_e32 v11, v91
	s_waitcnt lgkmcnt(8)
	v_mfma_f32_32x32x16_bf16 v[64:79], v[148:151], v[2:5], v[64:79]
	v_add_f32_e32 v0, v11, v0
	v_cvt_pk_bf16_f32 v125, v10, v11
	v_exp_f32_e32 v10, v92
	s_waitcnt lgkmcnt(6)
	v_mfma_f32_32x32x16_bf16 v[48:63], v[144:147], v[6:9], v[48:63]
	v_add_f32_e32 v0, v10, v0
	v_exp_f32_e32 v6, v93
	s_waitcnt lgkmcnt(4)
	v_mfma_f32_32x32x16_bf16 v[64:79], v[144:147], v[80:83], v[64:79]
	ds_read_b128 v[2:5], v88
	v_add_f32_e32 v0, v6, v0
	v_cvt_pk_bf16_f32 v126, v10, v6
	v_exp_f32_e32 v10, v94
	s_waitcnt lgkmcnt(3)
	v_mfma_f32_32x32x16_bf16 v[48:63], v[140:143], v[96:99], v[48:63]
	v_add_f32_e32 v0, v10, v0
	v_exp_f32_e32 v11, v95
	s_waitcnt lgkmcnt(1)
	v_mfma_f32_32x32x16_bf16 v[64:79], v[140:143], v[84:87], v[64:79]
	ds_read_b128 v[6:9], v88 offset:2048
	v_add_f32_e32 v0, v11, v0
	v_cvt_pk_bf16_f32 v127, v10, v11
	s_add_i32 s51, s47, 0x2000
	s_cmpk_lg_i32 s47, 0x4000
	s_waitcnt vmcnt(4) lgkmcnt(0)
	s_barrier
	s_cselect_b32 s51, s51, 0
	s_add_i32 s74, s46, 0x2000
	s_cmpk_lg_i32 s46, 0x6000
	s_cselect_b32 s76, s74, 0
	v_add_f32_e32 v0, v229, v0
	v_lshl_add_u32 v14, s49, 1, v218
	ds_read_b128 v[10:13], v88 offset:4096
	ds_read_b128 v[80:83], v88 offset:6144
	ds_read_b64_tr_b16 v[156:157], v14
	ds_read_b64_tr_b16 v[158:159], v14 offset:512
	v_lshl_add_u32 v15, s76, 1, v228
	s_waitcnt lgkmcnt(5)
	v_mfma_f32_32x32x16_bf16 v[92:107], v[2:5], v[120:123], 0
	s_add_u32 s74, s44, 0xff040000
	s_addc_u32 s75, s45, -1
	s_add_i32 s77, s48, s72
	s_mov_b32 s48, m0
	s_mov_b32 m0, s77
	s_nop 0
	global_load_lds_dwordx4 v226, s[74:75]
	s_mov_b32 m0, s48
	ds_read_b128 v[2:5], v88 offset:512
	ds_read_b128 v[160:163], v88 offset:2560
	ds_read_b64_tr_b16 v[164:165], v14 offset:4096
	ds_read_b64_tr_b16 v[166:167], v14 offset:4608
	s_waitcnt lgkmcnt(8)
	v_mfma_f32_32x32x16_bf16 v[92:107], v[6:9], v[116:119], v[92:107]
	s_add_u32 s48, s44, 0xff040080
	s_addc_u32 s49, s45, -1
	s_add_i32 s74, s77, 0x2000
	s_mov_b32 s75, m0
	s_mov_b32 m0, s74
	s_nop 0
	global_load_lds_dwordx4 v226, s[48:49]
	s_mov_b32 m0, s75
	ds_read_b128 v[6:9], v88 offset:4608
	ds_read_b128 v[168:171], v88 offset:6656
	ds_read_b64_tr_b16 v[172:173], v14 offset:1024
	ds_read_b64_tr_b16 v[174:175], v14 offset:1536
	s_waitcnt lgkmcnt(11)
	v_mfma_f32_32x32x16_bf16 v[92:107], v[10:13], v[112:115], v[92:107]
	ds_read_b64_tr_b16 v[10:11], v14 offset:5120
	ds_read_b64_tr_b16 v[12:13], v14 offset:5632
	s_waitcnt lgkmcnt(12)
	v_mfma_f32_32x32x16_bf16 v[92:107], v[80:83], v[108:111], v[92:107]
	s_lshl_b32 s48, s51, 1
	s_add_i32 s42, s42, 2
	s_add_i32 s74, s48, s73
	s_mov_b32 s48, m0
	s_mov_b32 m0, s74
	s_nop 0
	global_load_lds_dwordx4 v227, s[44:45]
	s_mov_b32 m0, s48
	s_add_u32 s48, s44, 0x80
	s_addc_u32 s49, s45, 0
	s_addk_i32 s74, 0x2000
	s_mov_b32 s75, m0
	s_mov_b32 m0, s74
	s_nop 0
	global_load_lds_dwordx4 v227, s[48:49]
	s_mov_b32 m0, s75
	v_exp_f32_e32 v140, v92
	v_exp_f32_e32 v144, v93
	v_exp_f32_e32 v148, v94
	v_exp_f32_e32 v149, v95
	s_waitcnt lgkmcnt(9)
	v_mfma_f32_32x32x16_bf16 v[80:95], v[2:5], v[120:123], 0
	ds_read_b64_tr_b16 v[2:3], v14 offset:2048
	ds_read_b64_tr_b16 v[4:5], v14 offset:2560
	v_add_f32_e32 v152, 0, v140
	v_add_f32_e32 v152, v144, v152
	v_add_f32_e32 v152, v148, v152
	v_add_f32_e32 v176, v149, v152
	v_cvt_pk_bf16_f32 v152, v140, v144
	v_cvt_pk_bf16_f32 v153, v148, v149
	v_exp_f32_e32 v140, v96
	v_exp_f32_e32 v144, v97
	v_exp_f32_e32 v148, v98
	s_waitcnt lgkmcnt(10)
	v_mfma_f32_32x32x16_bf16 v[80:95], v[160:163], v[116:119], v[80:95]
	v_exp_f32_e32 v149, v99
	ds_read_b64_tr_b16 v[96:97], v14 offset:6144
	ds_read_b64_tr_b16 v[98:99], v14 offset:6656
	v_add_f32_e32 v154, v140, v176
	v_add_f32_e32 v154, v144, v154
	v_add_f32_e32 v154, v148, v154
	v_add_f32_e32 v160, v149, v154
	v_cvt_pk_bf16_f32 v154, v140, v144
	v_cvt_pk_bf16_f32 v155, v148, v149
	v_exp_f32_e32 v100, v100
	v_exp_f32_e32 v101, v101
	v_exp_f32_e32 v102, v102
	s_waitcnt lgkmcnt(9)
	v_mfma_f32_32x32x16_bf16 v[80:95], v[6:9], v[112:115], v[80:95]
	v_exp_f32_e32 v103, v103
	ds_read_b64_tr_b16 v[6:7], v14 offset:3072
	ds_read_b64_tr_b16 v[8:9], v14 offset:3584
	v_add_f32_e32 v140, v100, v160
	v_add_f32_e32 v140, v101, v140
	v_add_f32_e32 v140, v102, v140
	v_add_f32_e32 v140, v103, v140
	v_cvt_pk_bf16_f32 v148, v100, v101
	v_cvt_pk_bf16_f32 v149, v102, v103
	v_exp_f32_e32 v104, v104
	v_exp_f32_e32 v105, v105
	v_exp_f32_e32 v106, v106
	s_waitcnt lgkmcnt(10)
	v_mfma_f32_32x32x16_bf16 v[80:95], v[168:171], v[108:111], v[80:95]
	v_exp_f32_e32 v107, v107
	ds_read_b64_tr_b16 v[100:101], v14 offset:7168
	ds_read_b64_tr_b16 v[102:103], v14 offset:7680
	v_add_f32_e32 v140, v104, v140
	v_add_f32_e32 v140, v105, v140
	v_add_f32_e32 v140, v106, v140
	v_add_f32_e32 v140, v107, v140
	v_cvt_pk_bf16_f32 v150, v104, v105
	v_cvt_pk_bf16_f32 v151, v106, v107
	s_nop 1
	v_mfma_f32_32x32x16_bf16 v[16:31], v[136:139], v[156:159], v[16:31]
	v_exp_f32_e32 v80, v80
	ds_read_b64_tr_b16 v[104:105], v14 offset:8192
	ds_read_b64_tr_b16 v[106:107], v14 offset:8704
	v_add_f32_e32 v140, v80, v140
	v_mfma_f32_32x32x16_bf16 v[32:47], v[136:139], v[164:167], v[32:47]
	v_exp_f32_e32 v81, v81
	ds_read_b64_tr_b16 v[156:157], v14 offset:12288
	ds_read_b64_tr_b16 v[158:159], v14 offset:12800
	v_add_f32_e32 v140, v81, v140
	v_cvt_pk_bf16_f32 v144, v80, v81
	s_waitcnt lgkmcnt(14)
	v_mfma_f32_32x32x16_bf16 v[16:31], v[132:135], v[172:175], v[16:31]
	v_exp_f32_e32 v80, v82
	ds_read_b64_tr_b16 v[160:161], v14 offset:9216
	ds_read_b64_tr_b16 v[162:163], v14 offset:9728
	v_add_f32_e32 v81, v80, v140
	s_waitcnt lgkmcnt(14)
	v_mfma_f32_32x32x16_bf16 v[32:47], v[132:135], v[10:13], v[32:47]
	v_exp_f32_e32 v82, v83
	ds_read_b64_tr_b16 v[10:11], v14 offset:13312
	ds_read_b64_tr_b16 v[12:13], v14 offset:13824
	v_add_f32_e32 v81, v82, v81
	v_cvt_pk_bf16_f32 v145, v80, v82
	s_waitcnt lgkmcnt(14)
	v_mfma_f32_32x32x16_bf16 v[16:31], v[128:131], v[2:5], v[16:31]
	v_exp_f32_e32 v84, v84
	ds_read_b64_tr_b16 v[2:3], v14 offset:10240
	ds_read_b64_tr_b16 v[4:5], v14 offset:10752
	v_add_f32_e32 v140, v84, v81
	s_waitcnt lgkmcnt(14)
	v_mfma_f32_32x32x16_bf16 v[32:47], v[128:131], v[96:99], v[32:47]
	v_exp_f32_e32 v85, v85
	ds_read_b64_tr_b16 v[80:81], v14 offset:14336
	ds_read_b64_tr_b16 v[82:83], v14 offset:14848
	v_add_f32_e32 v96, v85, v140
	v_cvt_pk_bf16_f32 v146, v84, v85
	s_waitcnt lgkmcnt(14)
	v_mfma_f32_32x32x16_bf16 v[16:31], v[124:127], v[6:9], v[16:31]
	v_exp_f32_e32 v97, v86
	ds_read_b64_tr_b16 v[6:7], v14 offset:11264
	ds_read_b64_tr_b16 v[8:9], v14 offset:11776
	v_add_f32_e32 v96, v97, v96
	s_waitcnt lgkmcnt(14)
	v_mfma_f32_32x32x16_bf16 v[32:47], v[124:127], v[100:103], v[32:47]
	v_exp_f32_e32 v98, v87
	ds_read_b64_tr_b16 v[84:85], v14 offset:15360
	ds_read_b64_tr_b16 v[86:87], v14 offset:15872
	v_add_f32_e32 v14, v98, v96
	v_cvt_pk_bf16_f32 v147, v97, v98
	v_exp_f32_e32 v88, v88
	s_waitcnt lgkmcnt(14)
	v_mfma_f32_32x32x16_bf16 v[48:63], v[136:139], v[104:107], v[48:63]
	v_add_f32_e32 v14, v88, v14
	v_exp_f32_e32 v89, v89
	s_waitcnt lgkmcnt(12)
	v_mfma_f32_32x32x16_bf16 v[64:79], v[136:139], v[156:159], v[64:79]
	v_add_f32_e32 v14, v89, v14
	v_cvt_pk_bf16_f32 v140, v88, v89
	v_exp_f32_e32 v88, v90
	s_waitcnt lgkmcnt(10)
	v_mfma_f32_32x32x16_bf16 v[48:63], v[132:135], v[160:163], v[48:63]
	v_add_f32_e32 v14, v88, v14
	v_exp_f32_e32 v89, v91
	s_waitcnt lgkmcnt(8)
	v_mfma_f32_32x32x16_bf16 v[64:79], v[132:135], v[10:13], v[64:79]
	v_add_f32_e32 v14, v89, v14
	v_cvt_pk_bf16_f32 v141, v88, v89
	v_exp_f32_e32 v10, v92
	s_waitcnt lgkmcnt(6)
	v_mfma_f32_32x32x16_bf16 v[48:63], v[128:131], v[2:5], v[48:63]
	v_add_f32_e32 v2, v10, v14
	s_waitcnt lgkmcnt(4)
	v_mfma_f32_32x32x16_bf16 v[64:79], v[128:131], v[80:83], v[64:79]
	v_exp_f32_e32 v3, v93
	ds_read_b128 v[156:159], v15
	v_add_f32_e32 v2, v3, v2
	v_cvt_pk_bf16_f32 v142, v10, v3
	v_exp_f32_e32 v3, v94
	s_waitcnt lgkmcnt(3)
	v_mfma_f32_32x32x16_bf16 v[48:63], v[124:127], v[6:9], v[48:63]
	v_add_f32_e32 v2, v3, v2
	s_waitcnt lgkmcnt(1)
	v_mfma_f32_32x32x16_bf16 v[64:79], v[124:127], v[84:87], v[64:79]
	v_exp_f32_e32 v4, v95
	ds_read_b128 v[160:163], v15 offset:2048
	v_add_f32_e32 v2, v4, v2
	v_cvt_pk_bf16_f32 v143, v3, v4
	s_add_i32 s48, s51, 0x2000
	s_cmpk_lg_i32 s51, 0x4000
	s_cselect_b32 s74, s48, 0
	s_add_i32 s48, s76, 0x2000
	s_cmpk_lg_i32 s76, 0x6000
	s_waitcnt vmcnt(4) lgkmcnt(0)
	s_barrier
	s_cselect_b32 s75, s48, 0
	s_add_u32 s44, s44, 0x40000
	s_addc_u32 s45, s45, 0
	v_add_f32_e32 v229, v0, v2
	s_cmp_ge_i32 s42, s43
	s_mov_b32 s48, s47
	s_mov_b32 s77, s46
	s_cbranch_scc0 .LBB0_429
	s_add_i32 s43, s42, 1
	s_cmp_lt_i32 s43, s50
	s_mov_b64 s[44:45], -1
	s_cbranch_scc1 .LBB0_432
